# PRE (row stats + bf16 copy): four rows per wave loaded together instead of one serialized round trip per row (both instances); composed gate-weight tiles batched
# speedup vs baseline: 1.0043x; 1.0037x over previous
.LBB0_501:
	v_add_co_u32_e32 v40, vcc, 0xffffd000, v22
	s_nop 1
	v_addc_co_u32_e32 v41, vcc, -1, v23, vcc
	v_add_co_u32_e32 v42, vcc, 0xffffe000, v22
	s_nop 1
	v_addc_co_u32_e32 v43, vcc, -1, v23, vcc
	v_add_co_u32_e32 v44, vcc, 0xfffff000, v22
	s_nop 1
	v_addc_co_u32_e32 v45, vcc, -1, v23, vcc
	global_load_dwordx4 v[48:51], v[40:41], off offset:-3072
	global_load_dwordx4 v[52:55], v[40:41], off offset:-2048
	global_load_dwordx4 v[56:59], v[40:41], off offset:-1024
	global_load_dwordx4 v[60:63], v[40:41], off
	global_load_dwordx4 v[64:67], v[42:43], off offset:-3072
	global_load_dwordx4 v[68:71], v[42:43], off offset:-2048
	global_load_dwordx4 v[72:75], v[42:43], off offset:-1024
	global_load_dwordx4 v[76:79], v[42:43], off
	global_load_dwordx4 v[80:83], v[44:45], off offset:-3072
	global_load_dwordx4 v[84:87], v[44:45], off offset:-2048
	global_load_dwordx4 v[88:91], v[44:45], off offset:-1024
	global_load_dwordx4 v[92:95], v[44:45], off
	global_load_dwordx4 v[96:99], v[22:23], off offset:-3072
	global_load_dwordx4 v[100:103], v[22:23], off offset:-2048
	global_load_dwordx4 v[104:107], v[22:23], off offset:-1024
	global_load_dwordx4 v[108:111], v[22:23], off
	v_lshl_add_u64 v[124:125], s[82:83], 0, v[20:21]
	v_lshl_add_u64 v[126:127], s[82:83], 0, v[24:25]
	v_add_co_u32_e32 v118, vcc, 0x1f500000, v124
	s_nop 1
	v_addc_co_u32_e32 v119, vcc, 0, v125, vcc
	v_add_co_u32_e32 v120, vcc, 0x19500000, v126
	s_nop 1
	v_addc_co_u32_e32 v121, vcc, 0, v127, vcc
	v_add_co_u32_e32 v122, vcc, 0x19501000, v126
	s_nop 1
	v_addc_co_u32_e32 v123, vcc, 0, v127, vcc
	s_waitcnt vmcnt(12)
	v_mul_f32_e32 v112, v49, v49
	v_mul_f32_e32 v113, v53, v53
	v_mul_f32_e32 v114, v57, v57
	v_fmac_f32_e32 v112, v48, v48
	v_fmac_f32_e32 v113, v52, v52
	v_mul_f32_e32 v115, v61, v61
	v_fmac_f32_e32 v114, v56, v56
	v_fmac_f32_e32 v112, v50, v50
	v_fmac_f32_e32 v113, v54, v54
	v_fmac_f32_e32 v115, v60, v60
	v_fmac_f32_e32 v114, v58, v58
	v_fmac_f32_e32 v112, v51, v51
	v_fmac_f32_e32 v113, v55, v55
	v_fmac_f32_e32 v115, v62, v62
	v_fmac_f32_e32 v114, v59, v59
	v_add_f32_e32 v112, v112, v113
	v_add_f32_e32 v112, v112, v114
	v_fmac_f32_e32 v115, v63, v63
	v_add_f32_e32 v112, v112, v115
	ds_bpermute_b32 v116, v30, v112
	s_waitcnt lgkmcnt(0)
	v_add_f32_e32 v112, v112, v116
	ds_bpermute_b32 v116, v31, v112
	s_waitcnt lgkmcnt(0)
	v_add_f32_e32 v112, v112, v116
	ds_bpermute_b32 v116, v32, v112
	s_waitcnt lgkmcnt(0)
	v_add_f32_e32 v112, v112, v116
	ds_bpermute_b32 v116, v33, v112
	s_waitcnt lgkmcnt(0)
	v_add_f32_e32 v112, v112, v116
	ds_bpermute_b32 v116, v34, v112
	s_waitcnt lgkmcnt(0)
	v_add_f32_e32 v112, v112, v116
	ds_bpermute_b32 v116, v35, v112
	s_and_saveexec_b64 s[20:21], s[4:5]
	s_waitcnt lgkmcnt(0)
	v_add_f32_e32 v112, v112, v116
	v_fmamk_f32 v112, v112, 0x3a800000, v19
	v_mul_f32_e32 v113, 0x4b800000, v112
	v_cmp_gt_f32_e64 s[6:7], s11, v112
	s_nop 1
	v_cndmask_b32_e64 v112, v112, v113, s[6:7]
	v_rsq_f32_e32 v113, v112
	s_nop 0
	v_mul_f32_e32 v114, 0x45800000, v113
	v_cndmask_b32_e64 v114, v113, v114, s[6:7]
	global_store_dword v[118:119], v114, off
	s_or_b64 exec, exec, s[20:21]
	s_waitcnt lgkmcnt(0)
	v_cvt_pk_bf16_f32 v48, v48, v49
	v_cvt_pk_bf16_f32 v49, v50, v51
	global_store_dwordx2 v[120:121], v[48:49], off
	v_cvt_pk_bf16_f32 v52, v52, v53
	v_cvt_pk_bf16_f32 v53, v54, v55
	global_store_dwordx2 v[120:121], v[52:53], off offset:512
	v_cvt_pk_bf16_f32 v56, v56, v57
	v_cvt_pk_bf16_f32 v57, v58, v59
	global_store_dwordx2 v[120:121], v[56:57], off offset:1024
	v_cvt_pk_bf16_f32 v60, v60, v61
	v_cvt_pk_bf16_f32 v61, v62, v63
	global_store_dwordx2 v[120:121], v[60:61], off offset:1536
	s_waitcnt vmcnt(13)
	v_mul_f32_e32 v112, v65, v65
	v_mul_f32_e32 v113, v69, v69
	v_mul_f32_e32 v114, v73, v73
	v_fmac_f32_e32 v112, v64, v64
	v_fmac_f32_e32 v113, v68, v68
	v_mul_f32_e32 v115, v77, v77
	v_fmac_f32_e32 v114, v72, v72
	v_fmac_f32_e32 v112, v66, v66
	v_fmac_f32_e32 v113, v70, v70
	v_fmac_f32_e32 v115, v76, v76
	v_fmac_f32_e32 v114, v74, v74
	v_fmac_f32_e32 v112, v67, v67
	v_fmac_f32_e32 v113, v71, v71
	v_fmac_f32_e32 v115, v78, v78
	v_fmac_f32_e32 v114, v75, v75
	v_add_f32_e32 v112, v112, v113
	v_add_f32_e32 v112, v112, v114
	v_fmac_f32_e32 v115, v79, v79
	v_add_f32_e32 v112, v112, v115
	ds_bpermute_b32 v116, v30, v112
	s_waitcnt lgkmcnt(0)
	v_add_f32_e32 v112, v112, v116
	ds_bpermute_b32 v116, v31, v112
	s_waitcnt lgkmcnt(0)
	v_add_f32_e32 v112, v112, v116
	ds_bpermute_b32 v116, v32, v112
	s_waitcnt lgkmcnt(0)
	v_add_f32_e32 v112, v112, v116
	ds_bpermute_b32 v116, v33, v112
	s_waitcnt lgkmcnt(0)
	v_add_f32_e32 v112, v112, v116
	ds_bpermute_b32 v116, v34, v112
	s_waitcnt lgkmcnt(0)
	v_add_f32_e32 v112, v112, v116
	ds_bpermute_b32 v116, v35, v112
	s_and_saveexec_b64 s[20:21], s[4:5]
	s_waitcnt lgkmcnt(0)
	v_add_f32_e32 v112, v112, v116
	v_fmamk_f32 v112, v112, 0x3a800000, v19
	v_mul_f32_e32 v113, 0x4b800000, v112
	v_cmp_gt_f32_e64 s[6:7], s11, v112
	s_nop 1
	v_cndmask_b32_e64 v112, v112, v113, s[6:7]
	v_rsq_f32_e32 v113, v112
	s_nop 0
	v_mul_f32_e32 v114, 0x45800000, v113
	v_cndmask_b32_e64 v114, v113, v114, s[6:7]
	global_store_dword v[118:119], v114, off offset:4
	s_or_b64 exec, exec, s[20:21]
	s_waitcnt lgkmcnt(0)
	v_cvt_pk_bf16_f32 v64, v64, v65
	v_cvt_pk_bf16_f32 v65, v66, v67
	global_store_dwordx2 v[120:121], v[64:65], off offset:2048
	v_cvt_pk_bf16_f32 v68, v68, v69
	v_cvt_pk_bf16_f32 v69, v70, v71
	global_store_dwordx2 v[120:121], v[68:69], off offset:2560
	v_cvt_pk_bf16_f32 v72, v72, v73
	v_cvt_pk_bf16_f32 v73, v74, v75
	global_store_dwordx2 v[120:121], v[72:73], off offset:3072
	v_cvt_pk_bf16_f32 v76, v76, v77
	v_cvt_pk_bf16_f32 v77, v78, v79
	global_store_dwordx2 v[120:121], v[76:77], off offset:3584
	s_waitcnt vmcnt(14)
	v_mul_f32_e32 v112, v81, v81
	v_mul_f32_e32 v113, v85, v85
	v_mul_f32_e32 v114, v89, v89
	v_fmac_f32_e32 v112, v80, v80
	v_fmac_f32_e32 v113, v84, v84
	v_mul_f32_e32 v115, v93, v93
	v_fmac_f32_e32 v114, v88, v88
	v_fmac_f32_e32 v112, v82, v82
	v_fmac_f32_e32 v113, v86, v86
	v_fmac_f32_e32 v115, v92, v92
	v_fmac_f32_e32 v114, v90, v90
	v_fmac_f32_e32 v112, v83, v83
	v_fmac_f32_e32 v113, v87, v87
	v_fmac_f32_e32 v115, v94, v94
	v_fmac_f32_e32 v114, v91, v91
	v_add_f32_e32 v112, v112, v113
	v_add_f32_e32 v112, v112, v114
	v_fmac_f32_e32 v115, v95, v95
	v_add_f32_e32 v112, v112, v115
	ds_bpermute_b32 v116, v30, v112
	s_waitcnt lgkmcnt(0)
	v_add_f32_e32 v112, v112, v116
	ds_bpermute_b32 v116, v31, v112
	s_waitcnt lgkmcnt(0)
	v_add_f32_e32 v112, v112, v116
	ds_bpermute_b32 v116, v32, v112
	s_waitcnt lgkmcnt(0)
	v_add_f32_e32 v112, v112, v116
	ds_bpermute_b32 v116, v33, v112
	s_waitcnt lgkmcnt(0)
	v_add_f32_e32 v112, v112, v116
	ds_bpermute_b32 v116, v34, v112
	s_waitcnt lgkmcnt(0)
	v_add_f32_e32 v112, v112, v116
	ds_bpermute_b32 v116, v35, v112
	s_and_saveexec_b64 s[20:21], s[4:5]
	s_waitcnt lgkmcnt(0)
	v_add_f32_e32 v112, v112, v116
	v_fmamk_f32 v112, v112, 0x3a800000, v19
	v_mul_f32_e32 v113, 0x4b800000, v112
	v_cmp_gt_f32_e64 s[6:7], s11, v112
	s_nop 1
	v_cndmask_b32_e64 v112, v112, v113, s[6:7]
	v_rsq_f32_e32 v113, v112
	s_nop 0
	v_mul_f32_e32 v114, 0x45800000, v113
	v_cndmask_b32_e64 v114, v113, v114, s[6:7]
	global_store_dword v[118:119], v114, off offset:8
	s_or_b64 exec, exec, s[20:21]
	s_waitcnt lgkmcnt(0)
	v_cvt_pk_bf16_f32 v80, v80, v81
	v_cvt_pk_bf16_f32 v81, v82, v83
	global_store_dwordx2 v[122:123], v[80:81], off
	v_cvt_pk_bf16_f32 v84, v84, v85
	v_cvt_pk_bf16_f32 v85, v86, v87
	global_store_dwordx2 v[122:123], v[84:85], off offset:512
	v_cvt_pk_bf16_f32 v88, v88, v89
	v_cvt_pk_bf16_f32 v89, v90, v91
	global_store_dwordx2 v[122:123], v[88:89], off offset:1024
	v_cvt_pk_bf16_f32 v92, v92, v93
	v_cvt_pk_bf16_f32 v93, v94, v95
	global_store_dwordx2 v[122:123], v[92:93], off offset:1536
	s_waitcnt vmcnt(15)
	v_mul_f32_e32 v112, v97, v97
	v_mul_f32_e32 v113, v101, v101
	v_mul_f32_e32 v114, v105, v105
	v_fmac_f32_e32 v112, v96, v96
	v_fmac_f32_e32 v113, v100, v100
	v_mul_f32_e32 v115, v109, v109
	v_fmac_f32_e32 v114, v104, v104
	v_fmac_f32_e32 v112, v98, v98
	v_fmac_f32_e32 v113, v102, v102
	v_fmac_f32_e32 v115, v108, v108
	v_fmac_f32_e32 v114, v106, v106
	v_fmac_f32_e32 v112, v99, v99
	v_fmac_f32_e32 v113, v103, v103
	v_fmac_f32_e32 v115, v110, v110
	v_fmac_f32_e32 v114, v107, v107
	v_add_f32_e32 v112, v112, v113
	v_add_f32_e32 v112, v112, v114
	v_fmac_f32_e32 v115, v111, v111
	v_add_f32_e32 v112, v112, v115
	ds_bpermute_b32 v116, v30, v112
	s_waitcnt lgkmcnt(0)
	v_add_f32_e32 v112, v112, v116
	ds_bpermute_b32 v116, v31, v112
	s_waitcnt lgkmcnt(0)
	v_add_f32_e32 v112, v112, v116
	ds_bpermute_b32 v116, v32, v112
	s_waitcnt lgkmcnt(0)
	v_add_f32_e32 v112, v112, v116
	ds_bpermute_b32 v116, v33, v112
	s_waitcnt lgkmcnt(0)
	v_add_f32_e32 v112, v112, v116
	ds_bpermute_b32 v116, v34, v112
	s_waitcnt lgkmcnt(0)
	v_add_f32_e32 v112, v112, v116
	ds_bpermute_b32 v116, v35, v112
	s_and_saveexec_b64 s[20:21], s[4:5]
	s_waitcnt lgkmcnt(0)
	v_add_f32_e32 v112, v112, v116
	v_fmamk_f32 v112, v112, 0x3a800000, v19
	v_mul_f32_e32 v113, 0x4b800000, v112
	v_cmp_gt_f32_e64 s[6:7], s11, v112
	s_nop 1
	v_cndmask_b32_e64 v112, v112, v113, s[6:7]
	v_rsq_f32_e32 v113, v112
	s_nop 0
	v_mul_f32_e32 v114, 0x45800000, v113
	v_cndmask_b32_e64 v114, v113, v114, s[6:7]
	global_store_dword v[118:119], v114, off offset:12
	s_or_b64 exec, exec, s[20:21]
	s_waitcnt lgkmcnt(0)
	v_cvt_pk_bf16_f32 v96, v96, v97
	v_cvt_pk_bf16_f32 v97, v98, v99
	global_store_dwordx2 v[122:123], v[96:97], off offset:2048
	v_cvt_pk_bf16_f32 v100, v100, v101
	v_cvt_pk_bf16_f32 v101, v102, v103
	global_store_dwordx2 v[122:123], v[100:101], off offset:2560
	v_cvt_pk_bf16_f32 v104, v104, v105
	v_cvt_pk_bf16_f32 v105, v106, v107
	global_store_dwordx2 v[122:123], v[104:105], off offset:3072
	v_cvt_pk_bf16_f32 v108, v108, v109
	v_cvt_pk_bf16_f32 v109, v110, v111
	global_store_dwordx2 v[122:123], v[108:109], off offset:3584
	v_add_u32_e32 v18, s10, v18
	v_cmp_lt_i32_e32 vcc, s24, v18
	v_lshl_add_u64 v[20:21], v[20:21], 0, s[12:13]
	v_lshl_add_u64 v[22:23], v[22:23], 0, s[14:15]
	s_or_b64 s[18:19], vcc, s[18:19]
	v_lshl_add_u64 v[24:25], v[24:25], 0, s[16:17]
	s_andn2_b64 exec, exec, s[18:19]
	s_cbranch_execnz .LBB0_501

.LBB0_531:
	v_add_co_u32_e32 v40, vcc, 0xffffd000, v22
	s_nop 1
	v_addc_co_u32_e32 v41, vcc, -1, v23, vcc
	v_add_co_u32_e32 v42, vcc, 0xffffe000, v22
	s_nop 1
	v_addc_co_u32_e32 v43, vcc, -1, v23, vcc
	v_add_co_u32_e32 v44, vcc, 0xfffff000, v22
	s_nop 1
	v_addc_co_u32_e32 v45, vcc, -1, v23, vcc
	global_load_dwordx4 v[48:51], v[40:41], off offset:-3072
	global_load_dwordx4 v[52:55], v[40:41], off offset:-2048
	global_load_dwordx4 v[56:59], v[40:41], off offset:-1024
	global_load_dwordx4 v[60:63], v[40:41], off
	global_load_dwordx4 v[64:67], v[42:43], off offset:-3072
	global_load_dwordx4 v[68:71], v[42:43], off offset:-2048
	global_load_dwordx4 v[72:75], v[42:43], off offset:-1024
	global_load_dwordx4 v[76:79], v[42:43], off
	global_load_dwordx4 v[80:83], v[44:45], off offset:-3072
	global_load_dwordx4 v[84:87], v[44:45], off offset:-2048
	global_load_dwordx4 v[88:91], v[44:45], off offset:-1024
	global_load_dwordx4 v[92:95], v[44:45], off
	global_load_dwordx4 v[96:99], v[22:23], off offset:-3072
	global_load_dwordx4 v[100:103], v[22:23], off offset:-2048
	global_load_dwordx4 v[104:107], v[22:23], off offset:-1024
	global_load_dwordx4 v[108:111], v[22:23], off
	v_lshl_add_u64 v[124:125], s[82:83], 0, v[20:21]
	v_lshl_add_u64 v[126:127], s[82:83], 0, v[24:25]
	v_add_co_u32_e32 v118, vcc, 0x1f500000, v124
	s_nop 1
	v_addc_co_u32_e32 v119, vcc, 0, v125, vcc
	v_add_co_u32_e32 v120, vcc, 0x19500000, v126
	s_nop 1
	v_addc_co_u32_e32 v121, vcc, 0, v127, vcc
	v_add_co_u32_e32 v122, vcc, 0x19501000, v126
	s_nop 1
	v_addc_co_u32_e32 v123, vcc, 0, v127, vcc
	s_waitcnt vmcnt(12)
	v_mul_f32_e32 v112, v49, v49
	v_mul_f32_e32 v113, v53, v53
	v_mul_f32_e32 v114, v57, v57
	v_fmac_f32_e32 v112, v48, v48
	v_fmac_f32_e32 v113, v52, v52
	v_mul_f32_e32 v115, v61, v61
	v_fmac_f32_e32 v114, v56, v56
	v_fmac_f32_e32 v112, v50, v50
	v_fmac_f32_e32 v113, v54, v54
	v_fmac_f32_e32 v115, v60, v60
	v_fmac_f32_e32 v114, v58, v58
	v_fmac_f32_e32 v112, v51, v51
	v_fmac_f32_e32 v113, v55, v55
	v_fmac_f32_e32 v115, v62, v62
	v_fmac_f32_e32 v114, v59, v59
	v_add_f32_e32 v112, v112, v113
	v_add_f32_e32 v112, v112, v114
	v_fmac_f32_e32 v115, v63, v63
	v_add_f32_e32 v112, v112, v115
	ds_bpermute_b32 v116, v16, v112
	s_waitcnt lgkmcnt(0)
	v_add_f32_e32 v112, v112, v116
	ds_bpermute_b32 v116, v30, v112
	s_waitcnt lgkmcnt(0)
	v_add_f32_e32 v112, v112, v116
	ds_bpermute_b32 v116, v31, v112
	s_waitcnt lgkmcnt(0)
	v_add_f32_e32 v112, v112, v116
	ds_bpermute_b32 v116, v32, v112
	s_waitcnt lgkmcnt(0)
	v_add_f32_e32 v112, v112, v116
	ds_bpermute_b32 v116, v33, v112
	s_waitcnt lgkmcnt(0)
	v_add_f32_e32 v112, v112, v116
	ds_bpermute_b32 v116, v34, v112
	s_and_saveexec_b64 s[12:13], s[0:1]
	s_waitcnt lgkmcnt(0)
	v_add_f32_e32 v112, v112, v116
	v_fmamk_f32 v112, v112, 0x3a800000, v236
	v_mul_f32_e32 v113, 0x4b800000, v112
	v_cmp_gt_f32_e64 s[38:39], s27, v112
	s_nop 1
	v_cndmask_b32_e64 v112, v112, v113, s[38:39]
	v_rsq_f32_e32 v113, v112
	s_nop 0
	v_mul_f32_e32 v114, 0x45800000, v113
	v_cndmask_b32_e64 v114, v113, v114, s[38:39]
	global_store_dword v[118:119], v114, off
	s_or_b64 exec, exec, s[12:13]
	s_waitcnt lgkmcnt(0)
	v_cvt_pk_bf16_f32 v48, v48, v49
	v_cvt_pk_bf16_f32 v49, v50, v51
	global_store_dwordx2 v[120:121], v[48:49], off
	v_cvt_pk_bf16_f32 v52, v52, v53
	v_cvt_pk_bf16_f32 v53, v54, v55
	global_store_dwordx2 v[120:121], v[52:53], off offset:512
	v_cvt_pk_bf16_f32 v56, v56, v57
	v_cvt_pk_bf16_f32 v57, v58, v59
	global_store_dwordx2 v[120:121], v[56:57], off offset:1024
	v_cvt_pk_bf16_f32 v60, v60, v61
	v_cvt_pk_bf16_f32 v61, v62, v63
	global_store_dwordx2 v[120:121], v[60:61], off offset:1536
	s_waitcnt vmcnt(13)
	v_mul_f32_e32 v112, v65, v65
	v_mul_f32_e32 v113, v69, v69
	v_mul_f32_e32 v114, v73, v73
	v_fmac_f32_e32 v112, v64, v64
	v_fmac_f32_e32 v113, v68, v68
	v_mul_f32_e32 v115, v77, v77
	v_fmac_f32_e32 v114, v72, v72
	v_fmac_f32_e32 v112, v66, v66
	v_fmac_f32_e32 v113, v70, v70
	v_fmac_f32_e32 v115, v76, v76
	v_fmac_f32_e32 v114, v74, v74
	v_fmac_f32_e32 v112, v67, v67
	v_fmac_f32_e32 v113, v71, v71
	v_fmac_f32_e32 v115, v78, v78
	v_fmac_f32_e32 v114, v75, v75
	v_add_f32_e32 v112, v112, v113
	v_add_f32_e32 v112, v112, v114
	v_fmac_f32_e32 v115, v79, v79
	v_add_f32_e32 v112, v112, v115
	ds_bpermute_b32 v116, v16, v112
	s_waitcnt lgkmcnt(0)
	v_add_f32_e32 v112, v112, v116
	ds_bpermute_b32 v116, v30, v112
	s_waitcnt lgkmcnt(0)
	v_add_f32_e32 v112, v112, v116
	ds_bpermute_b32 v116, v31, v112
	s_waitcnt lgkmcnt(0)
	v_add_f32_e32 v112, v112, v116
	ds_bpermute_b32 v116, v32, v112
	s_waitcnt lgkmcnt(0)
	v_add_f32_e32 v112, v112, v116
	ds_bpermute_b32 v116, v33, v112
	s_waitcnt lgkmcnt(0)
	v_add_f32_e32 v112, v112, v116
	ds_bpermute_b32 v116, v34, v112
	s_and_saveexec_b64 s[12:13], s[0:1]
	s_waitcnt lgkmcnt(0)
	v_add_f32_e32 v112, v112, v116
	v_fmamk_f32 v112, v112, 0x3a800000, v236
	v_mul_f32_e32 v113, 0x4b800000, v112
	v_cmp_gt_f32_e64 s[38:39], s27, v112
	s_nop 1
	v_cndmask_b32_e64 v112, v112, v113, s[38:39]
	v_rsq_f32_e32 v113, v112
	s_nop 0
	v_mul_f32_e32 v114, 0x45800000, v113
	v_cndmask_b32_e64 v114, v113, v114, s[38:39]
	global_store_dword v[118:119], v114, off offset:4
	s_or_b64 exec, exec, s[12:13]
	s_waitcnt lgkmcnt(0)
	v_cvt_pk_bf16_f32 v64, v64, v65
	v_cvt_pk_bf16_f32 v65, v66, v67
	global_store_dwordx2 v[120:121], v[64:65], off offset:2048
	v_cvt_pk_bf16_f32 v68, v68, v69
	v_cvt_pk_bf16_f32 v69, v70, v71
	global_store_dwordx2 v[120:121], v[68:69], off offset:2560
	v_cvt_pk_bf16_f32 v72, v72, v73
	v_cvt_pk_bf16_f32 v73, v74, v75
	global_store_dwordx2 v[120:121], v[72:73], off offset:3072
	v_cvt_pk_bf16_f32 v76, v76, v77
	v_cvt_pk_bf16_f32 v77, v78, v79
	global_store_dwordx2 v[120:121], v[76:77], off offset:3584
	s_waitcnt vmcnt(14)
	v_mul_f32_e32 v112, v81, v81
	v_mul_f32_e32 v113, v85, v85
	v_mul_f32_e32 v114, v89, v89
	v_fmac_f32_e32 v112, v80, v80
	v_fmac_f32_e32 v113, v84, v84
	v_mul_f32_e32 v115, v93, v93
	v_fmac_f32_e32 v114, v88, v88
	v_fmac_f32_e32 v112, v82, v82
	v_fmac_f32_e32 v113, v86, v86
	v_fmac_f32_e32 v115, v92, v92
	v_fmac_f32_e32 v114, v90, v90
	v_fmac_f32_e32 v112, v83, v83
	v_fmac_f32_e32 v113, v87, v87
	v_fmac_f32_e32 v115, v94, v94
	v_fmac_f32_e32 v114, v91, v91
	v_add_f32_e32 v112, v112, v113
	v_add_f32_e32 v112, v112, v114
	v_fmac_f32_e32 v115, v95, v95
	v_add_f32_e32 v112, v112, v115
	ds_bpermute_b32 v116, v16, v112
	s_waitcnt lgkmcnt(0)
	v_add_f32_e32 v112, v112, v116
	ds_bpermute_b32 v116, v30, v112
	s_waitcnt lgkmcnt(0)
	v_add_f32_e32 v112, v112, v116
	ds_bpermute_b32 v116, v31, v112
	s_waitcnt lgkmcnt(0)
	v_add_f32_e32 v112, v112, v116
	ds_bpermute_b32 v116, v32, v112
	s_waitcnt lgkmcnt(0)
	v_add_f32_e32 v112, v112, v116
	ds_bpermute_b32 v116, v33, v112
	s_waitcnt lgkmcnt(0)
	v_add_f32_e32 v112, v112, v116
	ds_bpermute_b32 v116, v34, v112
	s_and_saveexec_b64 s[12:13], s[0:1]
	s_waitcnt lgkmcnt(0)
	v_add_f32_e32 v112, v112, v116
	v_fmamk_f32 v112, v112, 0x3a800000, v236
	v_mul_f32_e32 v113, 0x4b800000, v112
	v_cmp_gt_f32_e64 s[38:39], s27, v112
	s_nop 1
	v_cndmask_b32_e64 v112, v112, v113, s[38:39]
	v_rsq_f32_e32 v113, v112
	s_nop 0
	v_mul_f32_e32 v114, 0x45800000, v113
	v_cndmask_b32_e64 v114, v113, v114, s[38:39]
	global_store_dword v[118:119], v114, off offset:8
	s_or_b64 exec, exec, s[12:13]
	s_waitcnt lgkmcnt(0)
	v_cvt_pk_bf16_f32 v80, v80, v81
	v_cvt_pk_bf16_f32 v81, v82, v83
	global_store_dwordx2 v[122:123], v[80:81], off
	v_cvt_pk_bf16_f32 v84, v84, v85
	v_cvt_pk_bf16_f32 v85, v86, v87
	global_store_dwordx2 v[122:123], v[84:85], off offset:512
	v_cvt_pk_bf16_f32 v88, v88, v89
	v_cvt_pk_bf16_f32 v89, v90, v91
	global_store_dwordx2 v[122:123], v[88:89], off offset:1024
	v_cvt_pk_bf16_f32 v92, v92, v93
	v_cvt_pk_bf16_f32 v93, v94, v95
	global_store_dwordx2 v[122:123], v[92:93], off offset:1536
	s_waitcnt vmcnt(15)
	v_mul_f32_e32 v112, v97, v97
	v_mul_f32_e32 v113, v101, v101
	v_mul_f32_e32 v114, v105, v105
	v_fmac_f32_e32 v112, v96, v96
	v_fmac_f32_e32 v113, v100, v100
	v_mul_f32_e32 v115, v109, v109
	v_fmac_f32_e32 v114, v104, v104
	v_fmac_f32_e32 v112, v98, v98
	v_fmac_f32_e32 v113, v102, v102
	v_fmac_f32_e32 v115, v108, v108
	v_fmac_f32_e32 v114, v106, v106
	v_fmac_f32_e32 v112, v99, v99
	v_fmac_f32_e32 v113, v103, v103
	v_fmac_f32_e32 v115, v110, v110
	v_fmac_f32_e32 v114, v107, v107
	v_add_f32_e32 v112, v112, v113
	v_add_f32_e32 v112, v112, v114
	v_fmac_f32_e32 v115, v111, v111
	v_add_f32_e32 v112, v112, v115
	ds_bpermute_b32 v116, v16, v112
	s_waitcnt lgkmcnt(0)
	v_add_f32_e32 v112, v112, v116
	ds_bpermute_b32 v116, v30, v112
	s_waitcnt lgkmcnt(0)
	v_add_f32_e32 v112, v112, v116
	ds_bpermute_b32 v116, v31, v112
	s_waitcnt lgkmcnt(0)
	v_add_f32_e32 v112, v112, v116
	ds_bpermute_b32 v116, v32, v112
	s_waitcnt lgkmcnt(0)
	v_add_f32_e32 v112, v112, v116
	ds_bpermute_b32 v116, v33, v112
	s_waitcnt lgkmcnt(0)
	v_add_f32_e32 v112, v112, v116
	ds_bpermute_b32 v116, v34, v112
	s_and_saveexec_b64 s[12:13], s[0:1]
	s_waitcnt lgkmcnt(0)
	v_add_f32_e32 v112, v112, v116
	v_fmamk_f32 v112, v112, 0x3a800000, v236
	v_mul_f32_e32 v113, 0x4b800000, v112
	v_cmp_gt_f32_e64 s[38:39], s27, v112
	s_nop 1
	v_cndmask_b32_e64 v112, v112, v113, s[38:39]
	v_rsq_f32_e32 v113, v112
	s_nop 0
	v_mul_f32_e32 v114, 0x45800000, v113
	v_cndmask_b32_e64 v114, v113, v114, s[38:39]
	global_store_dword v[118:119], v114, off offset:12
	s_or_b64 exec, exec, s[12:13]
	s_waitcnt lgkmcnt(0)
	v_cvt_pk_bf16_f32 v96, v96, v97
	v_cvt_pk_bf16_f32 v97, v98, v99
	global_store_dwordx2 v[122:123], v[96:97], off offset:2048
	v_cvt_pk_bf16_f32 v100, v100, v101
	v_cvt_pk_bf16_f32 v101, v102, v103
	global_store_dwordx2 v[122:123], v[100:101], off offset:2560
	v_cvt_pk_bf16_f32 v104, v104, v105
	v_cvt_pk_bf16_f32 v105, v106, v107
	global_store_dwordx2 v[122:123], v[104:105], off offset:3072
	v_cvt_pk_bf16_f32 v108, v108, v109
	v_cvt_pk_bf16_f32 v109, v110, v111
	global_store_dwordx2 v[122:123], v[108:109], off offset:3584
	v_readlane_b32 s12, v254, 16
	s_nop 1
	v_add_u32_e32 v18, s12, v18
	v_readlane_b32 s12, v254, 10
	v_readlane_b32 s13, v254, 11
	s_nop 1
	v_lshl_add_u64 v[20:21], v[20:21], 0, s[12:13]
	v_readlane_b32 s12, v254, 14
	v_readlane_b32 s13, v254, 15
	s_nop 1
	v_lshl_add_u64 v[22:23], v[22:23], 0, s[12:13]
	s_movk_i32 s2, 0x3fff
	v_cmp_lt_i32_e32 vcc, s2, v18
	v_readlane_b32 s12, v254, 18
	v_readlane_b32 s13, v254, 19
	s_nop 1
	v_lshl_add_u64 v[24:25], v[24:25], 0, s[12:13]
	s_or_b64 s[10:11], vcc, s[10:11]
	s_andn2_b64 exec, exec, s[10:11]
	s_cbranch_execnz .LBB0_531
